# cross-attention phase rewritten by hand: 256-token units, 2 token tiles per wave share each K/V LDS fragment, Q prefetch
# speedup vs baseline: 1.0334x; 1.0138x over previous
.LBB0_1648:
	v_readlane_b32 s0, v244, 47
	v_readlane_b32 s1, v244, 48
	v_readlane_b32 s2, v244, 49
	v_readlane_b32 s3, v244, 50
	s_cmp_gt_i32 s1, 6
	v_readlane_b32 s2, v243, 12
	s_cselect_b64 s[0:1], -1, 0
	v_readlane_b32 s3, v243, 13
	s_and_b64 s[2:3], s[2:3], s[0:1]
	s_andn2_b64 vcc, exec, s[2:3]
	s_branch .LBB0_1702

.LBB0_1947:
	v_readlane_b32 s4, v244, 47
	s_cmp_lt_i32 s4, 10
	s_cselect_b64 s[2:3], -1, 0
	s_and_b64 s[2:3], s[2:3], s[0:1]
	s_cmpk_lt_i32 s69, 0x600
	s_cselect_b64 s[0:1], -1, 0
	s_and_b64 s[0:1], s[2:3], s[0:1]
	s_andn2_b64 vcc, exec, s[0:1]
	v_readlane_b32 s5, v244, 48
	v_readlane_b32 s6, v244, 49
	v_readlane_b32 s7, v244, 50
	s_cbranch_vccnz .LBB0_1956
	v_and_b32_e32 v249, 63, v182
	v_readlane_b32 s4, v244, 6
	v_readlane_b32 s5, v244, 7
	v_readlane_b32 s6, v244, 39
	v_readlane_b32 s7, v244, 40
	v_readlane_b32 s8, v244, 41
	v_readlane_b32 s9, v244, 42
	v_lshlrev_b32_e32 v242, 2, v249
	s_nop 3
	global_load_dword v216, v242, s[6:7] offset:0
	global_load_dword v217, v242, s[6:7] offset:256
	global_load_dword v218, v242, s[6:7] offset:512
	global_load_dword v219, v242, s[6:7] offset:768
	global_load_dword v220, v242, s[8:9] offset:0
	global_load_dword v221, v242, s[8:9] offset:256
	global_load_dword v222, v242, s[8:9] offset:512
	global_load_dword v223, v242, s[8:9] offset:768
	v_and_b32_e32 v243, 15, v182
	v_bfe_u32 v245, v182, 4, 2
	v_lshl_or_b32 v246, s88, 4, v243
	v_lshlrev_b32_e32 v228, 11, v246
	v_lshl_add_u32 v238, v245, 3, v228
	v_lshl_add_u32 v228, v245, 4, v228
	v_add_u32_e32 v229, 0x40000, v228
	v_add_u32_e32 v239, 0x40000, v238
	v_lshlrev_b32_e32 v230, 4, v246
	v_mul_u32_u24_e32 v231, 528, v243
	v_lshl_add_u32 v232, v245, 3, v231
	v_lshl_add_u32 v231, v245, 4, v231
	v_lshrrev_b32_e32 v243, 5, v182
	v_and_b32_e32 v245, 31, v182
	v_lshlrev_b32_e32 v245, 4, v245
	v_lshl_add_u32 v224, v243, 11, v245
	v_mul_u32_u24_e32 v225, 5120, v243
	v_add_u32_e32 v225, v225, v245
	v_mul_u32_u24_e32 v226, 528, v243
	v_add_u32_e32 v226, v226, v245
	v_add_u32_e32 v227, 67584, v226
	v_xor_b32_e32 v236, 16, v249
	v_lshlrev_b32_e32 v236, 2, v236
	v_xor_b32_e32 v237, 32, v249
	v_lshlrev_b32_e32 v237, 2, v237
	v_mov_b32_e32 v181, 0x358637bd
	s_waitcnt vmcnt(0)
	v_mul_f32_e32 v216, v216, v220
	v_mul_f32_e32 v217, v217, v221
	v_mul_f32_e32 v218, v218, v222
	v_mul_f32_e32 v219, v219, v223
	v_max_f32_e64 v216, |v216|, |v217|
	v_max_f32_e64 v218, |v218|, |v219|
	v_max_f32_e32 v216, v216, v218
	v_xor_b32_e32 v242, 1, v249
	v_lshlrev_b32_e32 v242, 2, v242
	ds_bpermute_b32 v243, v242, v216
	s_waitcnt lgkmcnt(0)
	v_max_f32_e32 v216, v216, v243
	v_xor_b32_e32 v242, 2, v249
	v_lshlrev_b32_e32 v242, 2, v242
	ds_bpermute_b32 v243, v242, v216
	s_waitcnt lgkmcnt(0)
	v_max_f32_e32 v216, v216, v243
	v_xor_b32_e32 v242, 4, v249
	v_lshlrev_b32_e32 v242, 2, v242
	ds_bpermute_b32 v243, v242, v216
	s_waitcnt lgkmcnt(0)
	v_max_f32_e32 v216, v216, v243
	v_xor_b32_e32 v242, 8, v249
	v_lshlrev_b32_e32 v242, 2, v242
	ds_bpermute_b32 v243, v242, v216
	s_waitcnt lgkmcnt(0)
	v_max_f32_e32 v216, v216, v243
	v_xor_b32_e32 v242, 16, v249
	v_lshlrev_b32_e32 v242, 2, v242
	ds_bpermute_b32 v243, v242, v216
	s_waitcnt lgkmcnt(0)
	v_max_f32_e32 v216, v216, v243
	v_xor_b32_e32 v242, 32, v249
	v_lshlrev_b32_e32 v242, 2, v242
	ds_bpermute_b32 v243, v242, v216
	s_waitcnt lgkmcnt(0)
	v_max_f32_e32 v216, v216, v243
	v_mul_f32_e32 v180, 0x41b8aa3b, v216
	s_lshr_b32 s0, s69, 6
	s_mul_i32 s0, s0, 0x5556
	s_lshr_b32 s0, s0, 16
	s_mul_i32 s1, s0, 192
	s_sub_i32 s1, s69, s1
	s_lshl_b32 s11, s1, 19
	s_lshl_b32 s12, s0, 9
	s_add_u32 s11, s11, s12
	s_add_u32 s12, s11, 0xf000000
	s_add_u32 s10, s4, s12
	s_addc_u32 s11, s5, 0
	s_lshl_b32 s12, s1, 12
	s_lshl_b32 s13, s0, 2
	s_add_u32 s12, s12, s13
	s_add_u32 s12, s12, 0x1fa60000
	s_add_u32 s12, s4, s12
	s_addc_u32 s13, s5, 0
	global_load_dwordx4 v[0:3], v228, s[10:11] offset:0
	global_load_dwordx4 v[4:7], v228, s[10:11] offset:64
	global_load_dwordx4 v[8:11], v228, s[10:11] offset:128
	global_load_dwordx4 v[12:15], v228, s[10:11] offset:192
	global_load_dwordx4 v[16:19], v228, s[10:11] offset:256
	global_load_dwordx4 v[20:23], v228, s[10:11] offset:320
	global_load_dwordx4 v[24:27], v228, s[10:11] offset:384
	global_load_dwordx4 v[28:31], v228, s[10:11] offset:448
	global_load_dwordx4 v[32:35], v229, s[10:11] offset:0
	global_load_dwordx4 v[36:39], v229, s[10:11] offset:64
	global_load_dwordx4 v[40:43], v229, s[10:11] offset:128
	global_load_dwordx4 v[44:47], v229, s[10:11] offset:192
	global_load_dwordx4 v[48:51], v229, s[10:11] offset:256
	global_load_dwordx4 v[52:55], v229, s[10:11] offset:320
	global_load_dwordx4 v[56:59], v229, s[10:11] offset:384
	global_load_dwordx4 v[60:63], v229, s[10:11] offset:448
	global_load_dword v247, v230, s[12:13]
	global_load_dword v248, v230, s[12:13] offset:2048
.Lxa_unit:
	s_lshr_b32 s0, s69, 6
	s_mul_i32 s0, s0, 0x5556
	s_lshr_b32 s0, s0, 16
	s_mul_i32 s1, s0, 192
	s_sub_i32 s1, s69, s1
	s_lshr_b32 s10, s1, 5
	s_sub_i32 s11, s1, 64
	s_lshr_b32 s11, s11, 4
	s_add_i32 s11, s11, 2
	s_cmp_lt_u32 s1, 64
	s_cselect_b32 s10, s10, s11
	s_lshl_b32 s11, s10, 19
	s_lshl_b32 s12, s0, 9
	s_add_u32 s11, s11, s12
	s_add_u32 s11, s11, 0x19000000
	s_add_u32 s6, s4, s11
	s_addc_u32 s7, s5, 0
	s_mul_i32 s11, s0, 0x140000
	s_lshl_b32 s12, s10, 9
	s_add_u32 s11, s11, s12
	s_add_u32 s11, s11, 0x19800000
	s_add_u32 s8, s4, s11
	s_addc_u32 s9, s5, 0
	s_lshl_b32 s12, s1, 19
	s_lshl_b32 s13, s0, 9
	s_add_u32 s12, s12, s13
	s_add_u32 s12, s12, 0x9000000
	s_add_u32 s14, s4, s12
	s_addc_u32 s15, s5, 0
	global_load_dwordx4 v[128:131], v224, s[6:7]
	s_add_u32 s6, s6, 0x8000
	s_addc_u32 s7, s7, 0
	global_load_dwordx4 v[132:135], v224, s[6:7]
	s_add_u32 s6, s6, 0x8000
	s_addc_u32 s7, s7, 0
	global_load_dwordx4 v[136:139], v224, s[6:7]
	s_add_u32 s6, s6, 0x8000
	s_addc_u32 s7, s7, 0
	global_load_dwordx4 v[140:143], v224, s[6:7]
	s_add_u32 s6, s6, 0x8000
	s_addc_u32 s7, s7, 0
	global_load_dwordx4 v[144:147], v224, s[6:7]
	s_add_u32 s6, s6, 0x8000
	s_addc_u32 s7, s7, 0
	global_load_dwordx4 v[148:151], v224, s[6:7]
	s_add_u32 s6, s6, 0x8000
	s_addc_u32 s7, s7, 0
	global_load_dwordx4 v[152:155], v224, s[6:7]
	s_add_u32 s6, s6, 0x8000
	s_addc_u32 s7, s7, 0
	global_load_dwordx4 v[156:159], v224, s[6:7]
	s_add_u32 s6, s6, 0x8000
	s_addc_u32 s7, s7, 0
	global_load_dwordx4 v[184:187], v224, s[6:7]
	s_add_u32 s6, s6, 0x8000
	s_addc_u32 s7, s7, 0
	global_load_dwordx4 v[188:191], v224, s[6:7]
	s_add_u32 s6, s6, 0x8000
	s_addc_u32 s7, s7, 0
	global_load_dwordx4 v[192:195], v224, s[6:7]
	s_add_u32 s6, s6, 0x8000
	s_addc_u32 s7, s7, 0
	global_load_dwordx4 v[196:199], v224, s[6:7]
	s_add_u32 s6, s6, 0x8000
	s_addc_u32 s7, s7, 0
	global_load_dwordx4 v[200:203], v224, s[6:7]
	s_add_u32 s6, s6, 0x8000
	s_addc_u32 s7, s7, 0
	global_load_dwordx4 v[204:207], v224, s[6:7]
	s_add_u32 s6, s6, 0x8000
	s_addc_u32 s7, s7, 0
	global_load_dwordx4 v[208:211], v224, s[6:7]
	s_add_u32 s6, s6, 0x8000
	s_addc_u32 s7, s7, 0
	global_load_dwordx4 v[212:215], v224, s[6:7]
	s_waitcnt vmcnt(12)
	ds_write_b128 v226, v[128:131] offset:0
	ds_write_b128 v226, v[132:135] offset:8448
	ds_write_b128 v226, v[136:139] offset:16896
	ds_write_b128 v226, v[140:143] offset:25344
	s_waitcnt vmcnt(8)
	ds_write_b128 v226, v[144:147] offset:33792
	ds_write_b128 v226, v[148:151] offset:42240
	ds_write_b128 v226, v[152:155] offset:50688
	ds_write_b128 v226, v[156:159] offset:59136
	s_waitcnt vmcnt(4)
	ds_write_b128 v227, v[184:187] offset:0
	ds_write_b128 v227, v[188:191] offset:8448
	ds_write_b128 v227, v[192:195] offset:16896
	ds_write_b128 v227, v[196:199] offset:25344
	s_waitcnt vmcnt(0)
	ds_write_b128 v227, v[200:203] offset:33792
	ds_write_b128 v227, v[204:207] offset:42240
	ds_write_b128 v227, v[208:211] offset:50688
	ds_write_b128 v227, v[212:215] offset:59136
	s_waitcnt vmcnt(0)
	v_fmamk_f32 v178, v247, 0x3b800000, v181
	v_fmamk_f32 v179, v248, 0x3b800000, v181
	v_rsq_f32_e32 v178, v178
	v_rsq_f32_e32 v179, v179
	v_mov_b32_e32 v176, 0
	v_mov_b32_e32 v177, 0
	v_mul_f32_e32 v178, 0x3db8aa3b, v178
	v_mul_f32_e32 v179, 0x3db8aa3b, v179
	s_waitcnt lgkmcnt(0)
	s_barrier
	v_mov_b32_e32 v233, v231
	ds_read_b128 v[128:131], v233 offset:0
	ds_read_b128 v[132:135], v233 offset:64
	ds_read_b128 v[136:139], v233 offset:128
	ds_read_b128 v[140:143], v233 offset:192
	ds_read_b128 v[144:147], v233 offset:256
	ds_read_b128 v[148:151], v233 offset:320
	ds_read_b128 v[152:155], v233 offset:384
	ds_read_b128 v[156:159], v233 offset:448
	s_waitcnt lgkmcnt(0)
	ds_read_b128 v[184:187], v233 offset:8448
	ds_read_b128 v[188:191], v233 offset:8512
	ds_read_b128 v[192:195], v233 offset:8576
	ds_read_b128 v[196:199], v233 offset:8640
	ds_read_b128 v[200:203], v233 offset:8704
	ds_read_b128 v[204:207], v233 offset:8768
	ds_read_b128 v[208:211], v233 offset:8832
	ds_read_b128 v[212:215], v233 offset:8896
	v_mfma_f32_16x16x32_bf16 v[160:163], v[128:131], v[0:3], 0
	v_mfma_f32_16x16x32_bf16 v[164:167], v[128:131], v[32:35], 0
	v_mfma_f32_16x16x32_bf16 v[160:163], v[132:135], v[4:7], v[160:163]
	v_mfma_f32_16x16x32_bf16 v[164:167], v[132:135], v[36:39], v[164:167]
	v_mfma_f32_16x16x32_bf16 v[160:163], v[136:139], v[8:11], v[160:163]
	v_mfma_f32_16x16x32_bf16 v[164:167], v[136:139], v[40:43], v[164:167]
	v_mfma_f32_16x16x32_bf16 v[160:163], v[140:143], v[12:15], v[160:163]
	v_mfma_f32_16x16x32_bf16 v[164:167], v[140:143], v[44:47], v[164:167]
	v_mfma_f32_16x16x32_bf16 v[160:163], v[144:147], v[16:19], v[160:163]
	v_mfma_f32_16x16x32_bf16 v[164:167], v[144:147], v[48:51], v[164:167]
	v_mfma_f32_16x16x32_bf16 v[160:163], v[148:151], v[20:23], v[160:163]
	v_mfma_f32_16x16x32_bf16 v[164:167], v[148:151], v[52:55], v[164:167]
	v_mfma_f32_16x16x32_bf16 v[160:163], v[152:155], v[24:27], v[160:163]
	v_mfma_f32_16x16x32_bf16 v[164:167], v[152:155], v[56:59], v[164:167]
	v_mfma_f32_16x16x32_bf16 v[160:163], v[156:159], v[28:31], v[160:163]
	v_mfma_f32_16x16x32_bf16 v[164:167], v[156:159], v[60:63], v[164:167]
	s_waitcnt lgkmcnt(0)
	ds_read_b128 v[128:131], v233 offset:16896
	ds_read_b128 v[132:135], v233 offset:16960
	ds_read_b128 v[136:139], v233 offset:17024
	ds_read_b128 v[140:143], v233 offset:17088
	ds_read_b128 v[144:147], v233 offset:17152
	ds_read_b128 v[148:151], v233 offset:17216
	ds_read_b128 v[152:155], v233 offset:17280
	ds_read_b128 v[156:159], v233 offset:17344
	v_mfma_f32_16x16x32_bf16 v[168:171], v[184:187], v[0:3], 0
	v_fma_f32 v216, v160, v178, -v180
	v_fma_f32 v217, v161, v178, -v180
	v_mfma_f32_16x16x32_bf16 v[172:175], v[184:187], v[32:35], 0
	v_fma_f32 v218, v162, v178, -v180
	v_fma_f32 v219, v163, v178, -v180
	v_mfma_f32_16x16x32_bf16 v[168:171], v[188:191], v[4:7], v[168:171]
	v_exp_f32_e32 v216, v216
	v_exp_f32_e32 v217, v217
	v_mfma_f32_16x16x32_bf16 v[172:175], v[188:191], v[36:39], v[172:175]
	v_exp_f32_e32 v218, v218
	v_exp_f32_e32 v219, v219
	v_mfma_f32_16x16x32_bf16 v[168:171], v[192:195], v[8:11], v[168:171]
	v_fma_f32 v220, v164, v179, -v180
	v_fma_f32 v221, v165, v179, -v180
	v_mfma_f32_16x16x32_bf16 v[172:175], v[192:195], v[40:43], v[172:175]
	v_fma_f32 v222, v166, v179, -v180
	v_fma_f32 v223, v167, v179, -v180
	v_mfma_f32_16x16x32_bf16 v[168:171], v[196:199], v[12:15], v[168:171]
	v_exp_f32_e32 v220, v220
	v_exp_f32_e32 v221, v221
	v_mfma_f32_16x16x32_bf16 v[172:175], v[196:199], v[44:47], v[172:175]
	v_exp_f32_e32 v222, v222
	v_exp_f32_e32 v223, v223
	v_mfma_f32_16x16x32_bf16 v[168:171], v[200:203], v[16:19], v[168:171]
	v_add_f32_e32 v176, v176, v216
	v_add_f32_e32 v176, v176, v217
	v_mfma_f32_16x16x32_bf16 v[172:175], v[200:203], v[48:51], v[172:175]
	v_cvt_pk_bf16_f32 v64, v216, v217
	v_add_f32_e32 v176, v176, v218
	v_mfma_f32_16x16x32_bf16 v[168:171], v[204:207], v[20:23], v[168:171]
	v_add_f32_e32 v176, v176, v219
	v_cvt_pk_bf16_f32 v65, v218, v219
	v_mfma_f32_16x16x32_bf16 v[172:175], v[204:207], v[52:55], v[172:175]
	v_add_f32_e32 v177, v177, v220
	v_add_f32_e32 v177, v177, v221
	v_mfma_f32_16x16x32_bf16 v[168:171], v[208:211], v[24:27], v[168:171]
	v_cvt_pk_bf16_f32 v96, v220, v221
	v_add_f32_e32 v177, v177, v222
	v_mfma_f32_16x16x32_bf16 v[172:175], v[208:211], v[56:59], v[172:175]
	v_add_f32_e32 v177, v177, v223
	v_cvt_pk_bf16_f32 v97, v222, v223
	v_mfma_f32_16x16x32_bf16 v[168:171], v[212:215], v[28:31], v[168:171]
	v_mfma_f32_16x16x32_bf16 v[172:175], v[212:215], v[60:63], v[172:175]
	s_waitcnt lgkmcnt(0)
	ds_read_b128 v[184:187], v233 offset:25344
	ds_read_b128 v[188:191], v233 offset:25408
	ds_read_b128 v[192:195], v233 offset:25472
	ds_read_b128 v[196:199], v233 offset:25536
	ds_read_b128 v[200:203], v233 offset:25600
	ds_read_b128 v[204:207], v233 offset:25664
	ds_read_b128 v[208:211], v233 offset:25728
	ds_read_b128 v[212:215], v233 offset:25792
	v_mfma_f32_16x16x32_bf16 v[160:163], v[128:131], v[0:3], 0
	v_fma_f32 v216, v168, v178, -v180
	v_fma_f32 v217, v169, v178, -v180
	v_mfma_f32_16x16x32_bf16 v[164:167], v[128:131], v[32:35], 0
	v_fma_f32 v218, v170, v178, -v180
	v_fma_f32 v219, v171, v178, -v180
	v_mfma_f32_16x16x32_bf16 v[160:163], v[132:135], v[4:7], v[160:163]
	v_exp_f32_e32 v216, v216
	v_exp_f32_e32 v217, v217
	v_mfma_f32_16x16x32_bf16 v[164:167], v[132:135], v[36:39], v[164:167]
	v_exp_f32_e32 v218, v218
	v_exp_f32_e32 v219, v219
	v_mfma_f32_16x16x32_bf16 v[160:163], v[136:139], v[8:11], v[160:163]
	v_fma_f32 v220, v172, v179, -v180
	v_fma_f32 v221, v173, v179, -v180
	v_mfma_f32_16x16x32_bf16 v[164:167], v[136:139], v[40:43], v[164:167]
	v_fma_f32 v222, v174, v179, -v180
	v_fma_f32 v223, v175, v179, -v180
	v_mfma_f32_16x16x32_bf16 v[160:163], v[140:143], v[12:15], v[160:163]
	v_exp_f32_e32 v220, v220
	v_exp_f32_e32 v221, v221
	v_mfma_f32_16x16x32_bf16 v[164:167], v[140:143], v[44:47], v[164:167]
	v_exp_f32_e32 v222, v222
	v_exp_f32_e32 v223, v223
	v_mfma_f32_16x16x32_bf16 v[160:163], v[144:147], v[16:19], v[160:163]
	v_add_f32_e32 v176, v176, v216
	v_add_f32_e32 v176, v176, v217
	v_mfma_f32_16x16x32_bf16 v[164:167], v[144:147], v[48:51], v[164:167]
	v_cvt_pk_bf16_f32 v66, v216, v217
	v_add_f32_e32 v176, v176, v218
	v_mfma_f32_16x16x32_bf16 v[160:163], v[148:151], v[20:23], v[160:163]
	v_add_f32_e32 v176, v176, v219
	v_cvt_pk_bf16_f32 v67, v218, v219
	v_mfma_f32_16x16x32_bf16 v[164:167], v[148:151], v[52:55], v[164:167]
	v_add_f32_e32 v177, v177, v220
	v_add_f32_e32 v177, v177, v221
	v_mfma_f32_16x16x32_bf16 v[160:163], v[152:155], v[24:27], v[160:163]
	v_cvt_pk_bf16_f32 v98, v220, v221
	v_add_f32_e32 v177, v177, v222
	v_mfma_f32_16x16x32_bf16 v[164:167], v[152:155], v[56:59], v[164:167]
	v_add_f32_e32 v177, v177, v223
	v_cvt_pk_bf16_f32 v99, v222, v223
	v_mfma_f32_16x16x32_bf16 v[160:163], v[156:159], v[28:31], v[160:163]
	v_mfma_f32_16x16x32_bf16 v[164:167], v[156:159], v[60:63], v[164:167]
	s_waitcnt lgkmcnt(0)
	ds_read_b128 v[128:131], v233 offset:33792
	ds_read_b128 v[132:135], v233 offset:33856
	ds_read_b128 v[136:139], v233 offset:33920
	ds_read_b128 v[140:143], v233 offset:33984
	ds_read_b128 v[144:147], v233 offset:34048
	ds_read_b128 v[148:151], v233 offset:34112
	ds_read_b128 v[152:155], v233 offset:34176
	ds_read_b128 v[156:159], v233 offset:34240
	v_mfma_f32_16x16x32_bf16 v[168:171], v[184:187], v[0:3], 0
	v_fma_f32 v216, v160, v178, -v180
	v_fma_f32 v217, v161, v178, -v180
	v_mfma_f32_16x16x32_bf16 v[172:175], v[184:187], v[32:35], 0
	v_fma_f32 v218, v162, v178, -v180
	v_fma_f32 v219, v163, v178, -v180
	v_mfma_f32_16x16x32_bf16 v[168:171], v[188:191], v[4:7], v[168:171]
	v_exp_f32_e32 v216, v216
	v_exp_f32_e32 v217, v217
	v_mfma_f32_16x16x32_bf16 v[172:175], v[188:191], v[36:39], v[172:175]
	v_exp_f32_e32 v218, v218
	v_exp_f32_e32 v219, v219
	v_mfma_f32_16x16x32_bf16 v[168:171], v[192:195], v[8:11], v[168:171]
	v_fma_f32 v220, v164, v179, -v180
	v_fma_f32 v221, v165, v179, -v180
	v_mfma_f32_16x16x32_bf16 v[172:175], v[192:195], v[40:43], v[172:175]
	v_fma_f32 v222, v166, v179, -v180
	v_fma_f32 v223, v167, v179, -v180
	v_mfma_f32_16x16x32_bf16 v[168:171], v[196:199], v[12:15], v[168:171]
	v_exp_f32_e32 v220, v220
	v_exp_f32_e32 v221, v221
	v_mfma_f32_16x16x32_bf16 v[172:175], v[196:199], v[44:47], v[172:175]
	v_exp_f32_e32 v222, v222
	v_exp_f32_e32 v223, v223
	v_mfma_f32_16x16x32_bf16 v[168:171], v[200:203], v[16:19], v[168:171]
	v_add_f32_e32 v176, v176, v216
	v_add_f32_e32 v176, v176, v217
	v_mfma_f32_16x16x32_bf16 v[172:175], v[200:203], v[48:51], v[172:175]
	v_cvt_pk_bf16_f32 v68, v216, v217
	v_add_f32_e32 v176, v176, v218
	v_mfma_f32_16x16x32_bf16 v[168:171], v[204:207], v[20:23], v[168:171]
	v_add_f32_e32 v176, v176, v219
	v_cvt_pk_bf16_f32 v69, v218, v219
	v_mfma_f32_16x16x32_bf16 v[172:175], v[204:207], v[52:55], v[172:175]
	v_add_f32_e32 v177, v177, v220
	v_add_f32_e32 v177, v177, v221
	v_mfma_f32_16x16x32_bf16 v[168:171], v[208:211], v[24:27], v[168:171]
	v_cvt_pk_bf16_f32 v100, v220, v221
	v_add_f32_e32 v177, v177, v222
	v_mfma_f32_16x16x32_bf16 v[172:175], v[208:211], v[56:59], v[172:175]
	v_add_f32_e32 v177, v177, v223
	v_cvt_pk_bf16_f32 v101, v222, v223
	v_mfma_f32_16x16x32_bf16 v[168:171], v[212:215], v[28:31], v[168:171]
	v_mfma_f32_16x16x32_bf16 v[172:175], v[212:215], v[60:63], v[172:175]
	s_waitcnt lgkmcnt(0)
	ds_read_b128 v[184:187], v233 offset:42240
	ds_read_b128 v[188:191], v233 offset:42304
	ds_read_b128 v[192:195], v233 offset:42368
	ds_read_b128 v[196:199], v233 offset:42432
	ds_read_b128 v[200:203], v233 offset:42496
	ds_read_b128 v[204:207], v233 offset:42560
	ds_read_b128 v[208:211], v233 offset:42624
	ds_read_b128 v[212:215], v233 offset:42688
	v_mfma_f32_16x16x32_bf16 v[160:163], v[128:131], v[0:3], 0
	v_fma_f32 v216, v168, v178, -v180
	v_fma_f32 v217, v169, v178, -v180
	v_mfma_f32_16x16x32_bf16 v[164:167], v[128:131], v[32:35], 0
	v_fma_f32 v218, v170, v178, -v180
	v_fma_f32 v219, v171, v178, -v180
	v_mfma_f32_16x16x32_bf16 v[160:163], v[132:135], v[4:7], v[160:163]
	v_exp_f32_e32 v216, v216
	v_exp_f32_e32 v217, v217
	v_mfma_f32_16x16x32_bf16 v[164:167], v[132:135], v[36:39], v[164:167]
	v_exp_f32_e32 v218, v218
	v_exp_f32_e32 v219, v219
	v_mfma_f32_16x16x32_bf16 v[160:163], v[136:139], v[8:11], v[160:163]
	v_fma_f32 v220, v172, v179, -v180
	v_fma_f32 v221, v173, v179, -v180
	v_mfma_f32_16x16x32_bf16 v[164:167], v[136:139], v[40:43], v[164:167]
	v_fma_f32 v222, v174, v179, -v180
	v_fma_f32 v223, v175, v179, -v180
	v_mfma_f32_16x16x32_bf16 v[160:163], v[140:143], v[12:15], v[160:163]
	v_exp_f32_e32 v220, v220
	v_exp_f32_e32 v221, v221
	v_mfma_f32_16x16x32_bf16 v[164:167], v[140:143], v[44:47], v[164:167]
	v_exp_f32_e32 v222, v222
	v_exp_f32_e32 v223, v223
	v_mfma_f32_16x16x32_bf16 v[160:163], v[144:147], v[16:19], v[160:163]
	v_add_f32_e32 v176, v176, v216
	v_add_f32_e32 v176, v176, v217
	v_mfma_f32_16x16x32_bf16 v[164:167], v[144:147], v[48:51], v[164:167]
	v_cvt_pk_bf16_f32 v70, v216, v217
	v_add_f32_e32 v176, v176, v218
	v_mfma_f32_16x16x32_bf16 v[160:163], v[148:151], v[20:23], v[160:163]
	v_add_f32_e32 v176, v176, v219
	v_cvt_pk_bf16_f32 v71, v218, v219
	v_mfma_f32_16x16x32_bf16 v[164:167], v[148:151], v[52:55], v[164:167]
	v_add_f32_e32 v177, v177, v220
	v_add_f32_e32 v177, v177, v221
	v_mfma_f32_16x16x32_bf16 v[160:163], v[152:155], v[24:27], v[160:163]
	v_cvt_pk_bf16_f32 v102, v220, v221
	v_add_f32_e32 v177, v177, v222
	v_mfma_f32_16x16x32_bf16 v[164:167], v[152:155], v[56:59], v[164:167]
	v_add_f32_e32 v177, v177, v223
	v_cvt_pk_bf16_f32 v103, v222, v223
	v_mfma_f32_16x16x32_bf16 v[160:163], v[156:159], v[28:31], v[160:163]
	v_mfma_f32_16x16x32_bf16 v[164:167], v[156:159], v[60:63], v[164:167]
	s_waitcnt lgkmcnt(0)
	ds_read_b128 v[128:131], v233 offset:50688
	ds_read_b128 v[132:135], v233 offset:50752
	ds_read_b128 v[136:139], v233 offset:50816
	ds_read_b128 v[140:143], v233 offset:50880
	ds_read_b128 v[144:147], v233 offset:50944
	ds_read_b128 v[148:151], v233 offset:51008
	ds_read_b128 v[152:155], v233 offset:51072
	ds_read_b128 v[156:159], v233 offset:51136
	v_mfma_f32_16x16x32_bf16 v[168:171], v[184:187], v[0:3], 0
	v_fma_f32 v216, v160, v178, -v180
	v_fma_f32 v217, v161, v178, -v180
	v_mfma_f32_16x16x32_bf16 v[172:175], v[184:187], v[32:35], 0
	v_fma_f32 v218, v162, v178, -v180
	v_fma_f32 v219, v163, v178, -v180
	v_mfma_f32_16x16x32_bf16 v[168:171], v[188:191], v[4:7], v[168:171]
	v_exp_f32_e32 v216, v216
	v_exp_f32_e32 v217, v217
	v_mfma_f32_16x16x32_bf16 v[172:175], v[188:191], v[36:39], v[172:175]
	v_exp_f32_e32 v218, v218
	v_exp_f32_e32 v219, v219
	v_mfma_f32_16x16x32_bf16 v[168:171], v[192:195], v[8:11], v[168:171]
	v_fma_f32 v220, v164, v179, -v180
	v_fma_f32 v221, v165, v179, -v180
	v_mfma_f32_16x16x32_bf16 v[172:175], v[192:195], v[40:43], v[172:175]
	v_fma_f32 v222, v166, v179, -v180
	v_fma_f32 v223, v167, v179, -v180
	v_mfma_f32_16x16x32_bf16 v[168:171], v[196:199], v[12:15], v[168:171]
	v_exp_f32_e32 v220, v220
	v_exp_f32_e32 v221, v221
	v_mfma_f32_16x16x32_bf16 v[172:175], v[196:199], v[44:47], v[172:175]
	v_exp_f32_e32 v222, v222
	v_exp_f32_e32 v223, v223
	v_mfma_f32_16x16x32_bf16 v[168:171], v[200:203], v[16:19], v[168:171]
	v_add_f32_e32 v176, v176, v216
	v_add_f32_e32 v176, v176, v217
	v_mfma_f32_16x16x32_bf16 v[172:175], v[200:203], v[48:51], v[172:175]
	v_cvt_pk_bf16_f32 v72, v216, v217
	v_add_f32_e32 v176, v176, v218
	v_mfma_f32_16x16x32_bf16 v[168:171], v[204:207], v[20:23], v[168:171]
	v_add_f32_e32 v176, v176, v219
	v_cvt_pk_bf16_f32 v73, v218, v219
	v_mfma_f32_16x16x32_bf16 v[172:175], v[204:207], v[52:55], v[172:175]
	v_add_f32_e32 v177, v177, v220
	v_add_f32_e32 v177, v177, v221
	v_mfma_f32_16x16x32_bf16 v[168:171], v[208:211], v[24:27], v[168:171]
	v_cvt_pk_bf16_f32 v104, v220, v221
	v_add_f32_e32 v177, v177, v222
	v_mfma_f32_16x16x32_bf16 v[172:175], v[208:211], v[56:59], v[172:175]
	v_add_f32_e32 v177, v177, v223
	v_cvt_pk_bf16_f32 v105, v222, v223
	v_mfma_f32_16x16x32_bf16 v[168:171], v[212:215], v[28:31], v[168:171]
	v_mfma_f32_16x16x32_bf16 v[172:175], v[212:215], v[60:63], v[172:175]
	s_waitcnt lgkmcnt(0)
	v_add_u32_e32 v233, 59136, v233
	ds_read_b128 v[184:187], v233 offset:0
	ds_read_b128 v[188:191], v233 offset:64
	ds_read_b128 v[192:195], v233 offset:128
	ds_read_b128 v[196:199], v233 offset:192
	ds_read_b128 v[200:203], v233 offset:256
	ds_read_b128 v[204:207], v233 offset:320
	ds_read_b128 v[208:211], v233 offset:384
	ds_read_b128 v[212:215], v233 offset:448
	v_mfma_f32_16x16x32_bf16 v[160:163], v[128:131], v[0:3], 0
	v_fma_f32 v216, v168, v178, -v180
	v_fma_f32 v217, v169, v178, -v180
	v_mfma_f32_16x16x32_bf16 v[164:167], v[128:131], v[32:35], 0
	v_fma_f32 v218, v170, v178, -v180
	v_fma_f32 v219, v171, v178, -v180
	v_mfma_f32_16x16x32_bf16 v[160:163], v[132:135], v[4:7], v[160:163]
	v_exp_f32_e32 v216, v216
	v_exp_f32_e32 v217, v217
	v_mfma_f32_16x16x32_bf16 v[164:167], v[132:135], v[36:39], v[164:167]
	v_exp_f32_e32 v218, v218
	v_exp_f32_e32 v219, v219
	v_mfma_f32_16x16x32_bf16 v[160:163], v[136:139], v[8:11], v[160:163]
	v_fma_f32 v220, v172, v179, -v180
	v_fma_f32 v221, v173, v179, -v180
	v_mfma_f32_16x16x32_bf16 v[164:167], v[136:139], v[40:43], v[164:167]
	v_fma_f32 v222, v174, v179, -v180
	v_fma_f32 v223, v175, v179, -v180
	v_mfma_f32_16x16x32_bf16 v[160:163], v[140:143], v[12:15], v[160:163]
	v_exp_f32_e32 v220, v220
	v_exp_f32_e32 v221, v221
	v_mfma_f32_16x16x32_bf16 v[164:167], v[140:143], v[44:47], v[164:167]
	v_exp_f32_e32 v222, v222
	v_exp_f32_e32 v223, v223
	v_mfma_f32_16x16x32_bf16 v[160:163], v[144:147], v[16:19], v[160:163]
	v_add_f32_e32 v176, v176, v216
	v_add_f32_e32 v176, v176, v217
	v_mfma_f32_16x16x32_bf16 v[164:167], v[144:147], v[48:51], v[164:167]
	v_cvt_pk_bf16_f32 v74, v216, v217
	v_add_f32_e32 v176, v176, v218
	v_mfma_f32_16x16x32_bf16 v[160:163], v[148:151], v[20:23], v[160:163]
	v_add_f32_e32 v176, v176, v219
	v_cvt_pk_bf16_f32 v75, v218, v219
	v_mfma_f32_16x16x32_bf16 v[164:167], v[148:151], v[52:55], v[164:167]
	v_add_f32_e32 v177, v177, v220
	v_add_f32_e32 v177, v177, v221
	v_mfma_f32_16x16x32_bf16 v[160:163], v[152:155], v[24:27], v[160:163]
	v_cvt_pk_bf16_f32 v106, v220, v221
	v_add_f32_e32 v177, v177, v222
	v_mfma_f32_16x16x32_bf16 v[164:167], v[152:155], v[56:59], v[164:167]
	v_add_f32_e32 v177, v177, v223
	v_cvt_pk_bf16_f32 v107, v222, v223
	v_mfma_f32_16x16x32_bf16 v[160:163], v[156:159], v[28:31], v[160:163]
	v_mfma_f32_16x16x32_bf16 v[164:167], v[156:159], v[60:63], v[164:167]
	s_waitcnt lgkmcnt(0)
	ds_read_b128 v[128:131], v233 offset:8448
	ds_read_b128 v[132:135], v233 offset:8512
	ds_read_b128 v[136:139], v233 offset:8576
	ds_read_b128 v[140:143], v233 offset:8640
	ds_read_b128 v[144:147], v233 offset:8704
	ds_read_b128 v[148:151], v233 offset:8768
	ds_read_b128 v[152:155], v233 offset:8832
	ds_read_b128 v[156:159], v233 offset:8896
	v_mfma_f32_16x16x32_bf16 v[168:171], v[184:187], v[0:3], 0
	v_fma_f32 v216, v160, v178, -v180
	v_fma_f32 v217, v161, v178, -v180
	v_mfma_f32_16x16x32_bf16 v[172:175], v[184:187], v[32:35], 0
	v_fma_f32 v218, v162, v178, -v180
	v_fma_f32 v219, v163, v178, -v180
	v_mfma_f32_16x16x32_bf16 v[168:171], v[188:191], v[4:7], v[168:171]
	v_exp_f32_e32 v216, v216
	v_exp_f32_e32 v217, v217
	v_mfma_f32_16x16x32_bf16 v[172:175], v[188:191], v[36:39], v[172:175]
	v_exp_f32_e32 v218, v218
	v_exp_f32_e32 v219, v219
	v_mfma_f32_16x16x32_bf16 v[168:171], v[192:195], v[8:11], v[168:171]
	v_fma_f32 v220, v164, v179, -v180
	v_fma_f32 v221, v165, v179, -v180
	v_mfma_f32_16x16x32_bf16 v[172:175], v[192:195], v[40:43], v[172:175]
	v_fma_f32 v222, v166, v179, -v180
	v_fma_f32 v223, v167, v179, -v180
	v_mfma_f32_16x16x32_bf16 v[168:171], v[196:199], v[12:15], v[168:171]
	v_exp_f32_e32 v220, v220
	v_exp_f32_e32 v221, v221
	v_mfma_f32_16x16x32_bf16 v[172:175], v[196:199], v[44:47], v[172:175]
	v_exp_f32_e32 v222, v222
	v_exp_f32_e32 v223, v223
	v_mfma_f32_16x16x32_bf16 v[168:171], v[200:203], v[16:19], v[168:171]
	v_add_f32_e32 v176, v176, v216
	v_add_f32_e32 v176, v176, v217
	v_mfma_f32_16x16x32_bf16 v[172:175], v[200:203], v[48:51], v[172:175]
	v_cvt_pk_bf16_f32 v76, v216, v217
	v_add_f32_e32 v176, v176, v218
	v_mfma_f32_16x16x32_bf16 v[168:171], v[204:207], v[20:23], v[168:171]
	v_add_f32_e32 v176, v176, v219
	v_cvt_pk_bf16_f32 v77, v218, v219
	v_mfma_f32_16x16x32_bf16 v[172:175], v[204:207], v[52:55], v[172:175]
	v_add_f32_e32 v177, v177, v220
	v_add_f32_e32 v177, v177, v221
	v_mfma_f32_16x16x32_bf16 v[168:171], v[208:211], v[24:27], v[168:171]
	v_cvt_pk_bf16_f32 v108, v220, v221
	v_add_f32_e32 v177, v177, v222
	v_mfma_f32_16x16x32_bf16 v[172:175], v[208:211], v[56:59], v[172:175]
	v_add_f32_e32 v177, v177, v223
	v_cvt_pk_bf16_f32 v109, v222, v223
	v_mfma_f32_16x16x32_bf16 v[168:171], v[212:215], v[28:31], v[168:171]
	v_mfma_f32_16x16x32_bf16 v[172:175], v[212:215], v[60:63], v[172:175]
	s_waitcnt lgkmcnt(0)
	ds_read_b128 v[184:187], v233 offset:16896
	ds_read_b128 v[188:191], v233 offset:16960
	ds_read_b128 v[192:195], v233 offset:17024
	ds_read_b128 v[196:199], v233 offset:17088
	ds_read_b128 v[200:203], v233 offset:17152
	ds_read_b128 v[204:207], v233 offset:17216
	ds_read_b128 v[208:211], v233 offset:17280
	ds_read_b128 v[212:215], v233 offset:17344
	v_mfma_f32_16x16x32_bf16 v[160:163], v[128:131], v[0:3], 0
	v_fma_f32 v216, v168, v178, -v180
	v_fma_f32 v217, v169, v178, -v180
	v_mfma_f32_16x16x32_bf16 v[164:167], v[128:131], v[32:35], 0
	v_fma_f32 v218, v170, v178, -v180
	v_fma_f32 v219, v171, v178, -v180
	v_mfma_f32_16x16x32_bf16 v[160:163], v[132:135], v[4:7], v[160:163]
	v_exp_f32_e32 v216, v216
	v_exp_f32_e32 v217, v217
	v_mfma_f32_16x16x32_bf16 v[164:167], v[132:135], v[36:39], v[164:167]
	v_exp_f32_e32 v218, v218
	v_exp_f32_e32 v219, v219
	v_mfma_f32_16x16x32_bf16 v[160:163], v[136:139], v[8:11], v[160:163]
	v_fma_f32 v220, v172, v179, -v180
	v_fma_f32 v221, v173, v179, -v180
	v_mfma_f32_16x16x32_bf16 v[164:167], v[136:139], v[40:43], v[164:167]
	v_fma_f32 v222, v174, v179, -v180
	v_fma_f32 v223, v175, v179, -v180
	v_mfma_f32_16x16x32_bf16 v[160:163], v[140:143], v[12:15], v[160:163]
	v_exp_f32_e32 v220, v220
	v_exp_f32_e32 v221, v221
	v_mfma_f32_16x16x32_bf16 v[164:167], v[140:143], v[44:47], v[164:167]
	v_exp_f32_e32 v222, v222
	v_exp_f32_e32 v223, v223
	v_mfma_f32_16x16x32_bf16 v[160:163], v[144:147], v[16:19], v[160:163]
	v_add_f32_e32 v176, v176, v216
	v_add_f32_e32 v176, v176, v217
	v_mfma_f32_16x16x32_bf16 v[164:167], v[144:147], v[48:51], v[164:167]
	v_cvt_pk_bf16_f32 v78, v216, v217
	v_add_f32_e32 v176, v176, v218
	v_mfma_f32_16x16x32_bf16 v[160:163], v[148:151], v[20:23], v[160:163]
	v_add_f32_e32 v176, v176, v219
	v_cvt_pk_bf16_f32 v79, v218, v219
	v_mfma_f32_16x16x32_bf16 v[164:167], v[148:151], v[52:55], v[164:167]
	v_add_f32_e32 v177, v177, v220
	v_add_f32_e32 v177, v177, v221
	v_mfma_f32_16x16x32_bf16 v[160:163], v[152:155], v[24:27], v[160:163]
	v_cvt_pk_bf16_f32 v110, v220, v221
	v_add_f32_e32 v177, v177, v222
	v_mfma_f32_16x16x32_bf16 v[164:167], v[152:155], v[56:59], v[164:167]
	v_add_f32_e32 v177, v177, v223
	v_cvt_pk_bf16_f32 v111, v222, v223
	v_mfma_f32_16x16x32_bf16 v[160:163], v[156:159], v[28:31], v[160:163]
	v_mfma_f32_16x16x32_bf16 v[164:167], v[156:159], v[60:63], v[164:167]
	s_waitcnt lgkmcnt(0)
	ds_read_b128 v[128:131], v233 offset:25344
	ds_read_b128 v[132:135], v233 offset:25408
	ds_read_b128 v[136:139], v233 offset:25472
	ds_read_b128 v[140:143], v233 offset:25536
	ds_read_b128 v[144:147], v233 offset:25600
	ds_read_b128 v[148:151], v233 offset:25664
	ds_read_b128 v[152:155], v233 offset:25728
	ds_read_b128 v[156:159], v233 offset:25792
	v_mfma_f32_16x16x32_bf16 v[168:171], v[184:187], v[0:3], 0
	v_fma_f32 v216, v160, v178, -v180
	v_fma_f32 v217, v161, v178, -v180
	v_mfma_f32_16x16x32_bf16 v[172:175], v[184:187], v[32:35], 0
	v_fma_f32 v218, v162, v178, -v180
	v_fma_f32 v219, v163, v178, -v180
	v_mfma_f32_16x16x32_bf16 v[168:171], v[188:191], v[4:7], v[168:171]
	v_exp_f32_e32 v216, v216
	v_exp_f32_e32 v217, v217
	v_mfma_f32_16x16x32_bf16 v[172:175], v[188:191], v[36:39], v[172:175]
	v_exp_f32_e32 v218, v218
	v_exp_f32_e32 v219, v219
	v_mfma_f32_16x16x32_bf16 v[168:171], v[192:195], v[8:11], v[168:171]
	v_fma_f32 v220, v164, v179, -v180
	v_fma_f32 v221, v165, v179, -v180
	v_mfma_f32_16x16x32_bf16 v[172:175], v[192:195], v[40:43], v[172:175]
	v_fma_f32 v222, v166, v179, -v180
	v_fma_f32 v223, v167, v179, -v180
	v_mfma_f32_16x16x32_bf16 v[168:171], v[196:199], v[12:15], v[168:171]
	v_exp_f32_e32 v220, v220
	v_exp_f32_e32 v221, v221
	v_mfma_f32_16x16x32_bf16 v[172:175], v[196:199], v[44:47], v[172:175]
	v_exp_f32_e32 v222, v222
	v_exp_f32_e32 v223, v223
	v_mfma_f32_16x16x32_bf16 v[168:171], v[200:203], v[16:19], v[168:171]
	v_add_f32_e32 v176, v176, v216
	v_add_f32_e32 v176, v176, v217
	v_mfma_f32_16x16x32_bf16 v[172:175], v[200:203], v[48:51], v[172:175]
	v_cvt_pk_bf16_f32 v80, v216, v217
	v_add_f32_e32 v176, v176, v218
	v_mfma_f32_16x16x32_bf16 v[168:171], v[204:207], v[20:23], v[168:171]
	v_add_f32_e32 v176, v176, v219
	v_cvt_pk_bf16_f32 v81, v218, v219
	v_mfma_f32_16x16x32_bf16 v[172:175], v[204:207], v[52:55], v[172:175]
	v_add_f32_e32 v177, v177, v220
	v_add_f32_e32 v177, v177, v221
	v_mfma_f32_16x16x32_bf16 v[168:171], v[208:211], v[24:27], v[168:171]
	v_cvt_pk_bf16_f32 v112, v220, v221
	v_add_f32_e32 v177, v177, v222
	v_mfma_f32_16x16x32_bf16 v[172:175], v[208:211], v[56:59], v[172:175]
	v_add_f32_e32 v177, v177, v223
	v_cvt_pk_bf16_f32 v113, v222, v223
	v_mfma_f32_16x16x32_bf16 v[168:171], v[212:215], v[28:31], v[168:171]
	v_mfma_f32_16x16x32_bf16 v[172:175], v[212:215], v[60:63], v[172:175]
	s_waitcnt lgkmcnt(0)
	ds_read_b128 v[184:187], v233 offset:33792
	ds_read_b128 v[188:191], v233 offset:33856
	ds_read_b128 v[192:195], v233 offset:33920
	ds_read_b128 v[196:199], v233 offset:33984
	ds_read_b128 v[200:203], v233 offset:34048
	ds_read_b128 v[204:207], v233 offset:34112
	ds_read_b128 v[208:211], v233 offset:34176
	ds_read_b128 v[212:215], v233 offset:34240
	v_mfma_f32_16x16x32_bf16 v[160:163], v[128:131], v[0:3], 0
	v_fma_f32 v216, v168, v178, -v180
	v_fma_f32 v217, v169, v178, -v180
	v_mfma_f32_16x16x32_bf16 v[164:167], v[128:131], v[32:35], 0
	v_fma_f32 v218, v170, v178, -v180
	v_fma_f32 v219, v171, v178, -v180
	v_mfma_f32_16x16x32_bf16 v[160:163], v[132:135], v[4:7], v[160:163]
	v_exp_f32_e32 v216, v216
	v_exp_f32_e32 v217, v217
	v_mfma_f32_16x16x32_bf16 v[164:167], v[132:135], v[36:39], v[164:167]
	v_exp_f32_e32 v218, v218
	v_exp_f32_e32 v219, v219
	v_mfma_f32_16x16x32_bf16 v[160:163], v[136:139], v[8:11], v[160:163]
	v_fma_f32 v220, v172, v179, -v180
	v_fma_f32 v221, v173, v179, -v180
	v_mfma_f32_16x16x32_bf16 v[164:167], v[136:139], v[40:43], v[164:167]
	v_fma_f32 v222, v174, v179, -v180
	v_fma_f32 v223, v175, v179, -v180
	v_mfma_f32_16x16x32_bf16 v[160:163], v[140:143], v[12:15], v[160:163]
	v_exp_f32_e32 v220, v220
	v_exp_f32_e32 v221, v221
	v_mfma_f32_16x16x32_bf16 v[164:167], v[140:143], v[44:47], v[164:167]
	v_exp_f32_e32 v222, v222
	v_exp_f32_e32 v223, v223
	v_mfma_f32_16x16x32_bf16 v[160:163], v[144:147], v[16:19], v[160:163]
	v_add_f32_e32 v176, v176, v216
	v_add_f32_e32 v176, v176, v217
	v_mfma_f32_16x16x32_bf16 v[164:167], v[144:147], v[48:51], v[164:167]
	v_cvt_pk_bf16_f32 v82, v216, v217
	v_add_f32_e32 v176, v176, v218
	v_mfma_f32_16x16x32_bf16 v[160:163], v[148:151], v[20:23], v[160:163]
	v_add_f32_e32 v176, v176, v219
	v_cvt_pk_bf16_f32 v83, v218, v219
	v_mfma_f32_16x16x32_bf16 v[164:167], v[148:151], v[52:55], v[164:167]
	v_add_f32_e32 v177, v177, v220
	v_add_f32_e32 v177, v177, v221
	v_mfma_f32_16x16x32_bf16 v[160:163], v[152:155], v[24:27], v[160:163]
	v_cvt_pk_bf16_f32 v114, v220, v221
	v_add_f32_e32 v177, v177, v222
	v_mfma_f32_16x16x32_bf16 v[164:167], v[152:155], v[56:59], v[164:167]
	v_add_f32_e32 v177, v177, v223
	v_cvt_pk_bf16_f32 v115, v222, v223
	v_mfma_f32_16x16x32_bf16 v[160:163], v[156:159], v[28:31], v[160:163]
	v_mfma_f32_16x16x32_bf16 v[164:167], v[156:159], v[60:63], v[164:167]
	s_waitcnt lgkmcnt(0)
	ds_read_b128 v[128:131], v233 offset:42240
	ds_read_b128 v[132:135], v233 offset:42304
	ds_read_b128 v[136:139], v233 offset:42368
	ds_read_b128 v[140:143], v233 offset:42432
	ds_read_b128 v[144:147], v233 offset:42496
	ds_read_b128 v[148:151], v233 offset:42560
	ds_read_b128 v[152:155], v233 offset:42624
	ds_read_b128 v[156:159], v233 offset:42688
	v_mfma_f32_16x16x32_bf16 v[168:171], v[184:187], v[0:3], 0
	v_fma_f32 v216, v160, v178, -v180
	v_fma_f32 v217, v161, v178, -v180
	v_mfma_f32_16x16x32_bf16 v[172:175], v[184:187], v[32:35], 0
	v_fma_f32 v218, v162, v178, -v180
	v_fma_f32 v219, v163, v178, -v180
	v_mfma_f32_16x16x32_bf16 v[168:171], v[188:191], v[4:7], v[168:171]
	v_exp_f32_e32 v216, v216
	v_exp_f32_e32 v217, v217
	v_mfma_f32_16x16x32_bf16 v[172:175], v[188:191], v[36:39], v[172:175]
	v_exp_f32_e32 v218, v218
	v_exp_f32_e32 v219, v219
	v_mfma_f32_16x16x32_bf16 v[168:171], v[192:195], v[8:11], v[168:171]
	v_fma_f32 v220, v164, v179, -v180
	v_fma_f32 v221, v165, v179, -v180
	v_mfma_f32_16x16x32_bf16 v[172:175], v[192:195], v[40:43], v[172:175]
	v_fma_f32 v222, v166, v179, -v180
	v_fma_f32 v223, v167, v179, -v180
	v_mfma_f32_16x16x32_bf16 v[168:171], v[196:199], v[12:15], v[168:171]
	v_exp_f32_e32 v220, v220
	v_exp_f32_e32 v221, v221
	v_mfma_f32_16x16x32_bf16 v[172:175], v[196:199], v[44:47], v[172:175]
	v_exp_f32_e32 v222, v222
	v_exp_f32_e32 v223, v223
	v_mfma_f32_16x16x32_bf16 v[168:171], v[200:203], v[16:19], v[168:171]
	v_add_f32_e32 v176, v176, v216
	v_add_f32_e32 v176, v176, v217
	v_mfma_f32_16x16x32_bf16 v[172:175], v[200:203], v[48:51], v[172:175]
	v_cvt_pk_bf16_f32 v84, v216, v217
	v_add_f32_e32 v176, v176, v218
	v_mfma_f32_16x16x32_bf16 v[168:171], v[204:207], v[20:23], v[168:171]
	v_add_f32_e32 v176, v176, v219
	v_cvt_pk_bf16_f32 v85, v218, v219
	v_mfma_f32_16x16x32_bf16 v[172:175], v[204:207], v[52:55], v[172:175]
	v_add_f32_e32 v177, v177, v220
	v_add_f32_e32 v177, v177, v221
	v_mfma_f32_16x16x32_bf16 v[168:171], v[208:211], v[24:27], v[168:171]
	v_cvt_pk_bf16_f32 v116, v220, v221
	v_add_f32_e32 v177, v177, v222
	v_mfma_f32_16x16x32_bf16 v[172:175], v[208:211], v[56:59], v[172:175]
	v_add_f32_e32 v177, v177, v223
	v_cvt_pk_bf16_f32 v117, v222, v223
	v_mfma_f32_16x16x32_bf16 v[168:171], v[212:215], v[28:31], v[168:171]
	v_mfma_f32_16x16x32_bf16 v[172:175], v[212:215], v[60:63], v[172:175]
	s_waitcnt lgkmcnt(0)
	ds_read_b128 v[184:187], v233 offset:50688
	ds_read_b128 v[188:191], v233 offset:50752
	ds_read_b128 v[192:195], v233 offset:50816
	ds_read_b128 v[196:199], v233 offset:50880
	ds_read_b128 v[200:203], v233 offset:50944
	ds_read_b128 v[204:207], v233 offset:51008
	ds_read_b128 v[208:211], v233 offset:51072
	ds_read_b128 v[212:215], v233 offset:51136
	v_mfma_f32_16x16x32_bf16 v[160:163], v[128:131], v[0:3], 0
	v_fma_f32 v216, v168, v178, -v180
	v_fma_f32 v217, v169, v178, -v180
	v_mfma_f32_16x16x32_bf16 v[164:167], v[128:131], v[32:35], 0
	v_fma_f32 v218, v170, v178, -v180
	v_fma_f32 v219, v171, v178, -v180
	v_mfma_f32_16x16x32_bf16 v[160:163], v[132:135], v[4:7], v[160:163]
	v_exp_f32_e32 v216, v216
	v_exp_f32_e32 v217, v217
	v_mfma_f32_16x16x32_bf16 v[164:167], v[132:135], v[36:39], v[164:167]
	v_exp_f32_e32 v218, v218
	v_exp_f32_e32 v219, v219
	v_mfma_f32_16x16x32_bf16 v[160:163], v[136:139], v[8:11], v[160:163]
	v_fma_f32 v220, v172, v179, -v180
	v_fma_f32 v221, v173, v179, -v180
	v_mfma_f32_16x16x32_bf16 v[164:167], v[136:139], v[40:43], v[164:167]
	v_fma_f32 v222, v174, v179, -v180
	v_fma_f32 v223, v175, v179, -v180
	v_mfma_f32_16x16x32_bf16 v[160:163], v[140:143], v[12:15], v[160:163]
	v_exp_f32_e32 v220, v220
	v_exp_f32_e32 v221, v221
	v_mfma_f32_16x16x32_bf16 v[164:167], v[140:143], v[44:47], v[164:167]
	v_exp_f32_e32 v222, v222
	v_exp_f32_e32 v223, v223
	v_mfma_f32_16x16x32_bf16 v[160:163], v[144:147], v[16:19], v[160:163]
	v_add_f32_e32 v176, v176, v216
	v_add_f32_e32 v176, v176, v217
	v_mfma_f32_16x16x32_bf16 v[164:167], v[144:147], v[48:51], v[164:167]
	v_cvt_pk_bf16_f32 v86, v216, v217
	v_add_f32_e32 v176, v176, v218
	v_mfma_f32_16x16x32_bf16 v[160:163], v[148:151], v[20:23], v[160:163]
	v_add_f32_e32 v176, v176, v219
	v_cvt_pk_bf16_f32 v87, v218, v219
	v_mfma_f32_16x16x32_bf16 v[164:167], v[148:151], v[52:55], v[164:167]
	v_add_f32_e32 v177, v177, v220
	v_add_f32_e32 v177, v177, v221
	v_mfma_f32_16x16x32_bf16 v[160:163], v[152:155], v[24:27], v[160:163]
	v_cvt_pk_bf16_f32 v118, v220, v221
	v_add_f32_e32 v177, v177, v222
	v_mfma_f32_16x16x32_bf16 v[164:167], v[152:155], v[56:59], v[164:167]
	v_add_f32_e32 v177, v177, v223
	v_cvt_pk_bf16_f32 v119, v222, v223
	v_mfma_f32_16x16x32_bf16 v[160:163], v[156:159], v[28:31], v[160:163]
	v_mfma_f32_16x16x32_bf16 v[164:167], v[156:159], v[60:63], v[164:167]
	s_waitcnt lgkmcnt(0)
	v_add_u32_e32 v233, 59136, v233
	ds_read_b128 v[128:131], v233 offset:0
	ds_read_b128 v[132:135], v233 offset:64
	ds_read_b128 v[136:139], v233 offset:128
	ds_read_b128 v[140:143], v233 offset:192
	ds_read_b128 v[144:147], v233 offset:256
	ds_read_b128 v[148:151], v233 offset:320
	ds_read_b128 v[152:155], v233 offset:384
	ds_read_b128 v[156:159], v233 offset:448
	v_mfma_f32_16x16x32_bf16 v[168:171], v[184:187], v[0:3], 0
	v_fma_f32 v216, v160, v178, -v180
	v_fma_f32 v217, v161, v178, -v180
	v_mfma_f32_16x16x32_bf16 v[172:175], v[184:187], v[32:35], 0
	v_fma_f32 v218, v162, v178, -v180
	v_fma_f32 v219, v163, v178, -v180
	v_mfma_f32_16x16x32_bf16 v[168:171], v[188:191], v[4:7], v[168:171]
	v_exp_f32_e32 v216, v216
	v_exp_f32_e32 v217, v217
	v_mfma_f32_16x16x32_bf16 v[172:175], v[188:191], v[36:39], v[172:175]
	v_exp_f32_e32 v218, v218
	v_exp_f32_e32 v219, v219
	v_mfma_f32_16x16x32_bf16 v[168:171], v[192:195], v[8:11], v[168:171]
	v_fma_f32 v220, v164, v179, -v180
	v_fma_f32 v221, v165, v179, -v180
	v_mfma_f32_16x16x32_bf16 v[172:175], v[192:195], v[40:43], v[172:175]
	v_fma_f32 v222, v166, v179, -v180
	v_fma_f32 v223, v167, v179, -v180
	v_mfma_f32_16x16x32_bf16 v[168:171], v[196:199], v[12:15], v[168:171]
	v_exp_f32_e32 v220, v220
	v_exp_f32_e32 v221, v221
	v_mfma_f32_16x16x32_bf16 v[172:175], v[196:199], v[44:47], v[172:175]
	v_exp_f32_e32 v222, v222
	v_exp_f32_e32 v223, v223
	v_mfma_f32_16x16x32_bf16 v[168:171], v[200:203], v[16:19], v[168:171]
	v_add_f32_e32 v176, v176, v216
	v_add_f32_e32 v176, v176, v217
	v_mfma_f32_16x16x32_bf16 v[172:175], v[200:203], v[48:51], v[172:175]
	v_cvt_pk_bf16_f32 v88, v216, v217
	v_add_f32_e32 v176, v176, v218
	v_mfma_f32_16x16x32_bf16 v[168:171], v[204:207], v[20:23], v[168:171]
	v_add_f32_e32 v176, v176, v219
	v_cvt_pk_bf16_f32 v89, v218, v219
	v_mfma_f32_16x16x32_bf16 v[172:175], v[204:207], v[52:55], v[172:175]
	v_add_f32_e32 v177, v177, v220
	v_add_f32_e32 v177, v177, v221
	v_mfma_f32_16x16x32_bf16 v[168:171], v[208:211], v[24:27], v[168:171]
	v_cvt_pk_bf16_f32 v120, v220, v221
	v_add_f32_e32 v177, v177, v222
	v_mfma_f32_16x16x32_bf16 v[172:175], v[208:211], v[56:59], v[172:175]
	v_add_f32_e32 v177, v177, v223
	v_cvt_pk_bf16_f32 v121, v222, v223
	v_mfma_f32_16x16x32_bf16 v[168:171], v[212:215], v[28:31], v[168:171]
	v_mfma_f32_16x16x32_bf16 v[172:175], v[212:215], v[60:63], v[172:175]
	s_waitcnt lgkmcnt(0)
	ds_read_b128 v[184:187], v233 offset:8448
	ds_read_b128 v[188:191], v233 offset:8512
	ds_read_b128 v[192:195], v233 offset:8576
	ds_read_b128 v[196:199], v233 offset:8640
	ds_read_b128 v[200:203], v233 offset:8704
	ds_read_b128 v[204:207], v233 offset:8768
	ds_read_b128 v[208:211], v233 offset:8832
	ds_read_b128 v[212:215], v233 offset:8896
	v_mfma_f32_16x16x32_bf16 v[160:163], v[128:131], v[0:3], 0
	v_fma_f32 v216, v168, v178, -v180
	v_fma_f32 v217, v169, v178, -v180
	v_mfma_f32_16x16x32_bf16 v[164:167], v[128:131], v[32:35], 0
	v_fma_f32 v218, v170, v178, -v180
	v_fma_f32 v219, v171, v178, -v180
	v_mfma_f32_16x16x32_bf16 v[160:163], v[132:135], v[4:7], v[160:163]
	v_exp_f32_e32 v216, v216
	v_exp_f32_e32 v217, v217
	v_mfma_f32_16x16x32_bf16 v[164:167], v[132:135], v[36:39], v[164:167]
	v_exp_f32_e32 v218, v218
	v_exp_f32_e32 v219, v219
	v_mfma_f32_16x16x32_bf16 v[160:163], v[136:139], v[8:11], v[160:163]
	v_fma_f32 v220, v172, v179, -v180
	v_fma_f32 v221, v173, v179, -v180
	v_mfma_f32_16x16x32_bf16 v[164:167], v[136:139], v[40:43], v[164:167]
	v_fma_f32 v222, v174, v179, -v180
	v_fma_f32 v223, v175, v179, -v180
	v_mfma_f32_16x16x32_bf16 v[160:163], v[140:143], v[12:15], v[160:163]
	v_exp_f32_e32 v220, v220
	v_exp_f32_e32 v221, v221
	v_mfma_f32_16x16x32_bf16 v[164:167], v[140:143], v[44:47], v[164:167]
	v_exp_f32_e32 v222, v222
	v_exp_f32_e32 v223, v223
	v_mfma_f32_16x16x32_bf16 v[160:163], v[144:147], v[16:19], v[160:163]
	v_add_f32_e32 v176, v176, v216
	v_add_f32_e32 v176, v176, v217
	v_mfma_f32_16x16x32_bf16 v[164:167], v[144:147], v[48:51], v[164:167]
	v_cvt_pk_bf16_f32 v90, v216, v217
	v_add_f32_e32 v176, v176, v218
	v_mfma_f32_16x16x32_bf16 v[160:163], v[148:151], v[20:23], v[160:163]
	v_add_f32_e32 v176, v176, v219
	v_cvt_pk_bf16_f32 v91, v218, v219
	v_mfma_f32_16x16x32_bf16 v[164:167], v[148:151], v[52:55], v[164:167]
	v_add_f32_e32 v177, v177, v220
	v_add_f32_e32 v177, v177, v221
	v_mfma_f32_16x16x32_bf16 v[160:163], v[152:155], v[24:27], v[160:163]
	v_cvt_pk_bf16_f32 v122, v220, v221
	v_add_f32_e32 v177, v177, v222
	v_mfma_f32_16x16x32_bf16 v[164:167], v[152:155], v[56:59], v[164:167]
	v_add_f32_e32 v177, v177, v223
	v_cvt_pk_bf16_f32 v123, v222, v223
	v_mfma_f32_16x16x32_bf16 v[160:163], v[156:159], v[28:31], v[160:163]
	v_mfma_f32_16x16x32_bf16 v[164:167], v[156:159], v[60:63], v[164:167]
	s_waitcnt lgkmcnt(0)
	s_nop 6
	v_mfma_f32_16x16x32_bf16 v[168:171], v[184:187], v[0:3], 0
	v_fma_f32 v216, v160, v178, -v180
	v_fma_f32 v217, v161, v178, -v180
	v_mfma_f32_16x16x32_bf16 v[172:175], v[184:187], v[32:35], 0
	v_fma_f32 v218, v162, v178, -v180
	v_fma_f32 v219, v163, v178, -v180
	v_mfma_f32_16x16x32_bf16 v[168:171], v[188:191], v[4:7], v[168:171]
	v_exp_f32_e32 v216, v216
	v_exp_f32_e32 v217, v217
	v_mfma_f32_16x16x32_bf16 v[172:175], v[188:191], v[36:39], v[172:175]
	v_exp_f32_e32 v218, v218
	v_exp_f32_e32 v219, v219
	v_mfma_f32_16x16x32_bf16 v[168:171], v[192:195], v[8:11], v[168:171]
	v_fma_f32 v220, v164, v179, -v180
	v_fma_f32 v221, v165, v179, -v180
	v_mfma_f32_16x16x32_bf16 v[172:175], v[192:195], v[40:43], v[172:175]
	v_fma_f32 v222, v166, v179, -v180
	v_fma_f32 v223, v167, v179, -v180
	v_mfma_f32_16x16x32_bf16 v[168:171], v[196:199], v[12:15], v[168:171]
	v_exp_f32_e32 v220, v220
	v_exp_f32_e32 v221, v221
	v_mfma_f32_16x16x32_bf16 v[172:175], v[196:199], v[44:47], v[172:175]
	v_exp_f32_e32 v222, v222
	v_exp_f32_e32 v223, v223
	v_mfma_f32_16x16x32_bf16 v[168:171], v[200:203], v[16:19], v[168:171]
	v_add_f32_e32 v176, v176, v216
	v_add_f32_e32 v176, v176, v217
	v_mfma_f32_16x16x32_bf16 v[172:175], v[200:203], v[48:51], v[172:175]
	v_cvt_pk_bf16_f32 v92, v216, v217
	v_add_f32_e32 v176, v176, v218
	v_mfma_f32_16x16x32_bf16 v[168:171], v[204:207], v[20:23], v[168:171]
	v_add_f32_e32 v176, v176, v219
	v_cvt_pk_bf16_f32 v93, v218, v219
	v_mfma_f32_16x16x32_bf16 v[172:175], v[204:207], v[52:55], v[172:175]
	v_add_f32_e32 v177, v177, v220
	v_add_f32_e32 v177, v177, v221
	v_mfma_f32_16x16x32_bf16 v[168:171], v[208:211], v[24:27], v[168:171]
	v_cvt_pk_bf16_f32 v124, v220, v221
	v_add_f32_e32 v177, v177, v222
	v_mfma_f32_16x16x32_bf16 v[172:175], v[208:211], v[56:59], v[172:175]
	v_add_f32_e32 v177, v177, v223
	v_cvt_pk_bf16_f32 v125, v222, v223
	v_mfma_f32_16x16x32_bf16 v[168:171], v[212:215], v[28:31], v[168:171]
	v_mfma_f32_16x16x32_bf16 v[172:175], v[212:215], v[60:63], v[172:175]
	s_nop 7
	v_fma_f32 v216, v168, v178, -v180
	v_fma_f32 v217, v169, v178, -v180
	v_fma_f32 v218, v170, v178, -v180
	v_fma_f32 v219, v171, v178, -v180
	v_exp_f32_e32 v216, v216
	v_exp_f32_e32 v217, v217
	v_exp_f32_e32 v218, v218
	v_exp_f32_e32 v219, v219
	v_fma_f32 v220, v172, v179, -v180
	v_fma_f32 v221, v173, v179, -v180
	v_fma_f32 v222, v174, v179, -v180
	v_fma_f32 v223, v175, v179, -v180
	v_exp_f32_e32 v220, v220
	v_exp_f32_e32 v221, v221
	v_exp_f32_e32 v222, v222
	v_exp_f32_e32 v223, v223
	v_add_f32_e32 v176, v176, v216
	v_add_f32_e32 v176, v176, v217
	v_cvt_pk_bf16_f32 v94, v216, v217
	v_add_f32_e32 v176, v176, v218
	v_add_f32_e32 v176, v176, v219
	v_cvt_pk_bf16_f32 v95, v218, v219
	v_add_f32_e32 v177, v177, v220
	v_add_f32_e32 v177, v177, v221
	v_cvt_pk_bf16_f32 v126, v220, v221
	v_add_f32_e32 v177, v177, v222
	v_add_f32_e32 v177, v177, v223
	v_cvt_pk_bf16_f32 v127, v222, v223
	s_barrier
	global_load_dwordx4 v[128:131], v225, s[8:9]
	s_add_u32 s8, s8, 0x14000
	s_addc_u32 s9, s9, 0
	global_load_dwordx4 v[132:135], v225, s[8:9]
	s_add_u32 s8, s8, 0x14000
	s_addc_u32 s9, s9, 0
	global_load_dwordx4 v[136:139], v225, s[8:9]
	s_add_u32 s8, s8, 0x14000
	s_addc_u32 s9, s9, 0
	global_load_dwordx4 v[140:143], v225, s[8:9]
	s_add_u32 s8, s8, 0x14000
	s_addc_u32 s9, s9, 0
	global_load_dwordx4 v[144:147], v225, s[8:9]
	s_add_u32 s8, s8, 0x14000
	s_addc_u32 s9, s9, 0
	global_load_dwordx4 v[148:151], v225, s[8:9]
	s_add_u32 s8, s8, 0x14000
	s_addc_u32 s9, s9, 0
	global_load_dwordx4 v[152:155], v225, s[8:9]
	s_add_u32 s8, s8, 0x14000
	s_addc_u32 s9, s9, 0
	global_load_dwordx4 v[156:159], v225, s[8:9]
	s_add_u32 s8, s8, 0x14000
	s_addc_u32 s9, s9, 0
	global_load_dwordx4 v[184:187], v225, s[8:9]
	s_add_u32 s8, s8, 0x14000
	s_addc_u32 s9, s9, 0
	global_load_dwordx4 v[188:191], v225, s[8:9]
	s_add_u32 s8, s8, 0x14000
	s_addc_u32 s9, s9, 0
	global_load_dwordx4 v[192:195], v225, s[8:9]
	s_add_u32 s8, s8, 0x14000
	s_addc_u32 s9, s9, 0
	global_load_dwordx4 v[196:199], v225, s[8:9]
	s_add_u32 s8, s8, 0x14000
	s_addc_u32 s9, s9, 0
	global_load_dwordx4 v[200:203], v225, s[8:9]
	s_add_u32 s8, s8, 0x14000
	s_addc_u32 s9, s9, 0
	global_load_dwordx4 v[204:207], v225, s[8:9]
	s_add_u32 s8, s8, 0x14000
	s_addc_u32 s9, s9, 0
	global_load_dwordx4 v[208:211], v225, s[8:9]
	s_add_u32 s8, s8, 0x14000
	s_addc_u32 s9, s9, 0
	global_load_dwordx4 v[212:215], v225, s[8:9]
	s_add_i32 s16, s69, s86
	s_cmpk_lt_i32 s16, 0x300
	s_cselect_b32 s16, s16, s69
	s_lshr_b32 s0, s16, 6
	s_mul_i32 s0, s0, 0x5556
	s_lshr_b32 s0, s0, 16
	s_mul_i32 s1, s0, 192
	s_sub_i32 s1, s16, s1
	s_lshl_b32 s11, s1, 19
	s_lshl_b32 s12, s0, 9
	s_add_u32 s11, s11, s12
	s_add_u32 s12, s11, 0xf000000
	s_add_u32 s10, s4, s12
	s_addc_u32 s11, s5, 0
	s_lshl_b32 s12, s1, 12
	s_lshl_b32 s13, s0, 2
	s_add_u32 s12, s12, s13
	s_add_u32 s12, s12, 0x1fa60000
	s_add_u32 s12, s4, s12
	s_addc_u32 s13, s5, 0
	global_load_dwordx4 v[0:3], v228, s[10:11] offset:0
	global_load_dwordx4 v[4:7], v228, s[10:11] offset:64
	global_load_dwordx4 v[8:11], v228, s[10:11] offset:128
	global_load_dwordx4 v[12:15], v228, s[10:11] offset:192
	global_load_dwordx4 v[16:19], v228, s[10:11] offset:256
	global_load_dwordx4 v[20:23], v228, s[10:11] offset:320
	global_load_dwordx4 v[24:27], v228, s[10:11] offset:384
	global_load_dwordx4 v[28:31], v228, s[10:11] offset:448
	global_load_dwordx4 v[32:35], v229, s[10:11] offset:0
	global_load_dwordx4 v[36:39], v229, s[10:11] offset:64
	global_load_dwordx4 v[40:43], v229, s[10:11] offset:128
	global_load_dwordx4 v[44:47], v229, s[10:11] offset:192
	global_load_dwordx4 v[48:51], v229, s[10:11] offset:256
	global_load_dwordx4 v[52:55], v229, s[10:11] offset:320
	global_load_dwordx4 v[56:59], v229, s[10:11] offset:384
	global_load_dwordx4 v[60:63], v229, s[10:11] offset:448
	global_load_dword v247, v230, s[12:13]
	global_load_dword v248, v230, s[12:13] offset:2048
	ds_bpermute_b32 v242, v236, v176
	s_waitcnt lgkmcnt(0)
	v_add_f32_e32 v176, v176, v242
	ds_bpermute_b32 v242, v237, v176
	s_waitcnt lgkmcnt(0)
	v_add_f32_e32 v176, v176, v242
	ds_bpermute_b32 v242, v236, v177
	s_waitcnt lgkmcnt(0)
	v_add_f32_e32 v177, v177, v242
	ds_bpermute_b32 v242, v237, v177
	s_waitcnt lgkmcnt(0)
	v_add_f32_e32 v177, v177, v242
	v_rcp_f32_e32 v240, v176
	v_rcp_f32_e32 v241, v177
	s_waitcnt vmcnt(30)
	ds_write_b128 v226, v[128:131] offset:0
	ds_write_b128 v226, v[132:135] offset:8448
	ds_write_b128 v226, v[136:139] offset:16896
	ds_write_b128 v226, v[140:143] offset:25344
	s_waitcnt vmcnt(26)
	ds_write_b128 v226, v[144:147] offset:33792
	ds_write_b128 v226, v[148:151] offset:42240
	ds_write_b128 v226, v[152:155] offset:50688
	ds_write_b128 v226, v[156:159] offset:59136
	s_waitcnt vmcnt(22)
	ds_write_b128 v227, v[184:187] offset:0
	ds_write_b128 v227, v[188:191] offset:8448
	ds_write_b128 v227, v[192:195] offset:16896
	ds_write_b128 v227, v[196:199] offset:25344
	s_waitcnt vmcnt(18)
	ds_write_b128 v227, v[200:203] offset:33792
	ds_write_b128 v227, v[204:207] offset:42240
	ds_write_b128 v227, v[208:211] offset:50688
	ds_write_b128 v227, v[212:215] offset:59136
	s_waitcnt lgkmcnt(0)
	s_barrier
	s_mov_b32 s18, 0
	v_mov_b32_e32 v234, v232
	v_add_u32_e32 v235, 8448, v232
	ds_read_b64 v[128:129], v234 offset:0
	ds_read_b64 v[130:131], v234 offset:32
	ds_read_b64 v[132:133], v234 offset:64
	ds_read_b64 v[134:135], v234 offset:96
	ds_read_b64 v[136:137], v234 offset:128
	ds_read_b64 v[138:139], v234 offset:160
	ds_read_b64 v[140:141], v234 offset:192
	ds_read_b64 v[142:143], v234 offset:224
	ds_read_b64 v[144:145], v234 offset:256
	ds_read_b64 v[146:147], v234 offset:288
	ds_read_b64 v[148:149], v234 offset:320
	ds_read_b64 v[150:151], v234 offset:352
.Lxa_pv:
	ds_read_b64 v[152:153], v234 offset:384
	ds_read_b64 v[154:155], v234 offset:416
	s_waitcnt lgkmcnt(12)
	v_mfma_f32_16x16x32_bf16 v[160:163], v[128:131], v[64:67], 0
	v_mfma_f32_16x16x32_bf16 v[164:167], v[128:131], v[96:99], 0
	ds_read_b64 v[156:157], v234 offset:448
	ds_read_b64 v[158:159], v234 offset:480
	s_waitcnt lgkmcnt(12)
	v_mfma_f32_16x16x32_bf16 v[160:163], v[132:135], v[68:71], v[160:163]
	v_mfma_f32_16x16x32_bf16 v[164:167], v[132:135], v[100:103], v[164:167]
	ds_read_b64 v[128:129], v235 offset:0
	ds_read_b64 v[130:131], v235 offset:32
	s_waitcnt lgkmcnt(12)
	v_mfma_f32_16x16x32_bf16 v[160:163], v[136:139], v[72:75], v[160:163]
	v_mfma_f32_16x16x32_bf16 v[164:167], v[136:139], v[104:107], v[164:167]
	ds_read_b64 v[132:133], v235 offset:64
	ds_read_b64 v[134:135], v235 offset:96
	s_waitcnt lgkmcnt(12)
	v_mfma_f32_16x16x32_bf16 v[160:163], v[140:143], v[76:79], v[160:163]
	v_mfma_f32_16x16x32_bf16 v[164:167], v[140:143], v[108:111], v[164:167]
	ds_read_b64 v[136:137], v235 offset:128
	ds_read_b64 v[138:139], v235 offset:160
	s_waitcnt lgkmcnt(12)
	v_mfma_f32_16x16x32_bf16 v[160:163], v[144:147], v[80:83], v[160:163]
	v_mfma_f32_16x16x32_bf16 v[164:167], v[144:147], v[112:115], v[164:167]
	ds_read_b64 v[140:141], v235 offset:192
	ds_read_b64 v[142:143], v235 offset:224
	s_waitcnt lgkmcnt(12)
	v_mfma_f32_16x16x32_bf16 v[160:163], v[148:151], v[84:87], v[160:163]
	v_mfma_f32_16x16x32_bf16 v[164:167], v[148:151], v[116:119], v[164:167]
	ds_read_b64 v[144:145], v235 offset:256
	ds_read_b64 v[146:147], v235 offset:288
	s_waitcnt lgkmcnt(12)
	v_mfma_f32_16x16x32_bf16 v[160:163], v[152:155], v[88:91], v[160:163]
	v_mfma_f32_16x16x32_bf16 v[164:167], v[152:155], v[120:123], v[164:167]
	ds_read_b64 v[148:149], v235 offset:320
	ds_read_b64 v[150:151], v235 offset:352
	s_waitcnt lgkmcnt(12)
	v_mfma_f32_16x16x32_bf16 v[160:163], v[156:159], v[92:95], v[160:163]
	v_mfma_f32_16x16x32_bf16 v[164:167], v[156:159], v[124:127], v[164:167]
	s_add_i32 s18, s18, 1
	s_add_i32 s19, s18, 1
	s_and_b32 s19, s19, 15
	s_mul_i32 s19, s19, 8448
	s_cmp_lt_u32 s18, 16
	s_nop 2
	v_mul_f32_e32 v216, v160, v240
	v_mul_f32_e32 v217, v161, v240
	v_mul_f32_e32 v218, v162, v240
	v_mul_f32_e32 v219, v163, v240
	v_mul_f32_e32 v220, v164, v241
	v_mul_f32_e32 v221, v165, v241
	v_mul_f32_e32 v222, v166, v241
	v_mul_f32_e32 v223, v167, v241
	v_cvt_pk_bf16_f32 v216, v216, v217
	v_cvt_pk_bf16_f32 v217, v218, v219
	v_cvt_pk_bf16_f32 v218, v220, v221
	v_cvt_pk_bf16_f32 v219, v222, v223
	global_store_dwordx2 v238, v[216:217], s[14:15]
	global_store_dwordx2 v239, v[218:219], s[14:15]
	s_add_u32 s14, s14, 32
	s_addc_u32 s15, s15, 0
	v_mov_b32_e32 v234, v235
	v_add_u32_e32 v235, s19, v232
	s_cmp_lt_u32 s18, 16
	s_cbranch_scc1 .Lxa_pv
	s_waitcnt lgkmcnt(0)
	s_add_i32 s69, s69, s86
	s_cmpk_lt_i32 s69, 0x300
	s_barrier
	s_cbranch_scc1 .Lxa_unit
